# plus scan compute waves at raised priority (s_setprio 1 in their chunk loop, reset at phase end)
# speedup vs baseline: 1.0001x; 1.0001x over previous
; #define LAS __attribute__((address_space(3)))
; __device__ __forceinline__ unsigned pk2n(float lo, float hi) { return __builtin_bit_cast(unsigned, __builtin_convertvector((f32x2){lo, hi}, bf16v2)); }
; __device__ __forceinline__ void scan_phase(const Params& P, int l, LAS unsigned char* lds) {
;     ...
;                 if (it >= 0) {
;                     const LAS unsigned char* sl = lds + (it & 1) * SLOT + HGO;
;                     const int n0 = it * TS; const int plo = dir ? (n0 < 256 ? 256 - TS - n0 : TPB + 256 - TS - n0) : n0;
;                     u32x4 fq[4]; u32x2 fk[8]; f32x4 p15[8];
; #pragma unroll
;                     for (int j = 0; j < 4; ++j) fq[j] = *(const LAS u32x4*)(sl + (j * 64 + lane) * 16);
; #pragma unroll
;                     for (int m = 0; m < 8; ++m) { fk[m] = *(const LAS u32x2*)(sl + 4096 + (m * 64 + lane) * 8); p15[m] = *(const LAS f32x4*)(sl + 8704 + (16 * m + 4 * quad) * 4); }
;                     const u32x2 fa = *(const LAS u32x2*)(sl + 8192 + lane * 8); const f32x4 v4 = *(const LAS f32x4*)(sl + 9216 + lane * 16);
;                     bf16x8 sf[4];
; #pragma unroll
;                     for (int j = 0; j < 4; ++j) sf[j] = __builtin_bit_cast(bf16x8, (u32x4){pk2n(St[2 * j][0], St[2 * j][1]), pk2n(St[2 * j][2], St[2 * j][3]), pk2n(St[2 * j + 1][0], St[2 * j + 1][1]), pk2n(St[2 * j + 1][2], St[2 * j + 1][3])});
;                     const bf16x8 bv = __builtin_bit_cast(bf16x8, (u32x4){pk2n(v4[0], v4[1]), pk2n(v4[2], v4[3]), 0u, 0u});
;                     const bf16x8 FA8 = __builtin_bit_cast(bf16x8, (u32x4){fa[0], fa[1], 0u, 0u});
;                     f32x4 O = __builtin_amdgcn_mfma_f32_16x16x32_bf16(FA8, bv, zero4, 0, 0, 0);
; #pragma unroll
;                     for (int j = 0; j < 4; ++j) O = __builtin_amdgcn_mfma_f32_16x16x32_bf16(__builtin_bit_cast(bf16x8, fq[j]), sf[j], O, 0, 0, 0);
; #pragma unroll
;                     for (int m = 0; m < 8; ++m) St[m] = __builtin_amdgcn_mfma_f32_16x16x32_bf16(__builtin_bit_cast(bf16x8, (u32x4){fk[m][0], fk[m][1], 0u, 0u}), bv, St[m] * p15[m], 0, 0, 0);
; #pragma unroll
;                     for (int e = 0; e < 4; ++e) { const int t = 4 * quad + e; const int p = dir ? plo + TS - 1 - t : plo + t;
;                         Ohg[(rowbase + p) * 1024 + h * 128 + col0 + col] = (bf16_t)(pk2n(O[e], 0.f) & 0xffffu); }
.LBB0_779:
	s_cmp_lt_i32 s9, 0
	s_cbranch_scc1 .LBB0_778
	s_setprio 1
	s_bitcmp1_b32 s9, 0
	s_cselect_b32 s15, 0x6500, 0
	s_add_i32 s19, s15, 0
	v_add_u32_e32 v0, s19, v46
	v_add_u32_e32 v1, s19, v48
	v_add_u32_e32 v42, s19, v90
	ds_read_b128 v[38:41], v0 offset:15616
	ds_read_b128 v[60:63], v0 offset:16640
	ds_read_b128 v[64:67], v0 offset:17664
	ds_read_b128 v[68:71], v0 offset:18688
	v_add_u32_e32 v43, 0x100, v1
	ds_read_b128 v[72:75], v42 offset:24320
	ds_read_b128 v[76:79], v42 offset:24384
	ds_read2st64_b64 v[80:83], v43 offset0:38 offset1:39
	ds_read2st64_b64 v[84:87], v43 offset0:40 offset1:41
	ds_read_b128 v[100:103], v42 offset:24448
	ds_read_b128 v[104:107], v42 offset:24512
	ds_read_b64 v[108:109], v1 offset:23808
	ds_read_b128 v[112:115], v0 offset:24832
	v_mov_b32_e32 v110, v3
	v_mov_b32_e32 v111, v3
	v_mov_b32_e32 v2, v3
	v_cvt_pk_bf16_f32 v116, v16, v17
	s_waitcnt lgkmcnt(0)
	v_cvt_pk_bf16_f32 v0, v112, v113
	v_cvt_pk_bf16_f32 v1, v114, v115
	v_cvt_pk_bf16_f32 v117, v18, v19
	v_cvt_pk_bf16_f32 v118, v4, v5
	v_mfma_f32_16x16x32_bf16 v[108:111], v[108:111], v[0:3], 0
	v_cvt_pk_bf16_f32 v119, v6, v7
	v_cvt_pk_bf16_f32 v112, v8, v9
	v_cvt_pk_bf16_f32 v113, v10, v11
	v_mfma_f32_16x16x32_bf16 v[38:41], v[38:41], v[116:119], v[108:111]
	v_cvt_pk_bf16_f32 v114, v28, v29
	v_cvt_pk_bf16_f32 v115, v30, v31
	v_pk_mul_f32 v[6:7], v[6:7], v[78:79]
	s_nop 0
	v_cvt_pk_bf16_f32 v108, v12, v13
	v_mfma_f32_16x16x32_bf16 v[38:41], v[60:63], v[112:115], v[38:41]
	v_cvt_pk_bf16_f32 v109, v14, v15
	v_cvt_pk_bf16_f32 v110, v20, v21
	v_cvt_pk_bf16_f32 v111, v22, v23
	v_pk_mul_f32 v[4:5], v[4:5], v[76:77]
	v_cvt_pk_bf16_f32 v60, v32, v33
	v_mfma_f32_16x16x32_bf16 v[38:41], v[64:67], v[108:111], v[38:41]
	v_mov_b32_e32 v64, v82
	v_mov_b32_e32 v65, v83
	v_mov_b32_e32 v66, v3
	v_mov_b32_e32 v67, v3
	v_cvt_pk_bf16_f32 v61, v34, v35
	v_cvt_pk_bf16_f32 v62, v24, v25
	v_cvt_pk_bf16_f32 v63, v26, v27
	v_mfma_f32_16x16x32_bf16 v[4:7], v[64:67], v[0:3], v[4:7]
	v_mov_b32_e32 v64, v84
	v_mov_b32_e32 v65, v85
	v_pk_mul_f32 v[10:11], v[10:11], v[102:103]
	v_mfma_f32_16x16x32_bf16 v[38:41], v[68:71], v[60:63], v[38:41]
	v_mov_b32_e32 v60, v80
	v_mov_b32_e32 v61, v81
	v_mov_b32_e32 v62, v3
	v_mov_b32_e32 v63, v3
	v_pk_mul_f32 v[8:9], v[8:9], v[100:101]
	v_pk_mul_f32 v[18:19], v[18:19], v[74:75]
	v_pk_mul_f32 v[16:17], v[16:17], v[72:73]
	v_mfma_f32_16x16x32_bf16 v[8:11], v[64:67], v[0:3], v[8:11]
	v_mov_b32_e32 v64, v86
	v_mov_b32_e32 v65, v87
	v_pk_mul_f32 v[30:31], v[30:31], v[106:107]
	v_mfma_f32_16x16x32_bf16 v[16:19], v[60:63], v[0:3], v[16:19]
	ds_read_b128 v[60:63], v42 offset:24576
	ds_read2st64_b64 v[68:71], v43 offset0:42 offset1:43
	ds_read2st64_b64 v[72:75], v43 offset0:44 offset1:45
	v_pk_mul_f32 v[28:29], v[28:29], v[104:105]
	v_mov_b32_e32 v78, v3
	v_mov_b32_e32 v79, v3
	s_waitcnt lgkmcnt(1)
	v_mov_b32_e32 v76, v68
	v_mov_b32_e32 v77, v69
	v_mfma_f32_16x16x32_bf16 v[28:31], v[64:67], v[0:3], v[28:31]
	ds_read_b128 v[64:67], v42 offset:24640
	v_pk_mul_f32 v[14:15], v[14:15], v[62:63]
	v_pk_mul_f32 v[12:13], v[12:13], v[60:61]
	v_mov_b32_e32 v60, v70
	v_mov_b32_e32 v61, v71
	v_mov_b32_e32 v62, v3
	v_mov_b32_e32 v63, v3
	s_sub_i32 s15, s8, 64
	v_mfma_f32_16x16x32_bf16 v[12:15], v[76:79], v[0:3], v[12:15]
	ds_read_b128 v[68:71], v42 offset:24704
	ds_read_b128 v[76:79], v42 offset:24768
	s_waitcnt lgkmcnt(2)
	v_pk_mul_f32 v[22:23], v[22:23], v[66:67]
	v_pk_mul_f32 v[20:21], v[20:21], v[64:65]
	s_cmp_lt_u32 s9, 16
	v_mov_b32_e32 v64, v74
	v_mfma_f32_16x16x32_bf16 v[20:23], v[60:63], v[0:3], v[20:23]
	v_mov_b32_e32 v60, v72
	v_mov_b32_e32 v61, v73
	v_mov_b32_e32 v65, v75
	v_mov_b32_e32 v66, v3
	v_mov_b32_e32 v67, v3
	s_cselect_b32 s18, 0xf0, s93
	s_add_i32 s20, s18, s14
	s_and_b64 s[18:19], vcc, exec
	s_waitcnt lgkmcnt(1)
	v_pk_mul_f32 v[34:35], v[34:35], v[70:71]
	v_pk_mul_f32 v[32:33], v[32:33], v[68:69]
	s_waitcnt lgkmcnt(0)
	v_pk_mul_f32 v[26:27], v[26:27], v[78:79]
	v_pk_mul_f32 v[24:25], v[24:25], v[76:77]
	s_cselect_b32 s15, s15, s20
	v_mfma_f32_16x16x32_bf16 v[32:35], v[60:63], v[0:3], v[32:35]
	s_or_b32 s15, s15, 15
	v_cvt_pk_bf16_f32 v38, v38, s0
	v_mfma_f32_16x16x32_bf16 v[24:27], v[64:67], v[0:3], v[24:27]
	v_add_u32_e32 v2, s8, v45
	v_sub_u32_e32 v0, s15, v45
	v_subrev_u32_e32 v1, 64, v2
	v_cndmask_b32_e32 v0, v0, v1, vcc
	v_ashrrev_i32_e32 v1, 31, v0
	v_lshl_add_u64 v[0:1], s[16:17], 0, v[0:1]
	v_lshlrev_b64 v[0:1], 11, v[0:1]
	v_lshl_add_u64 v[0:1], v[36:37], 0, v[0:1]
	global_store_short v[0:1], v38, off
	s_and_b64 s[18:19], vcc, exec
	s_mov_b32 s18, 0xfffff800
	s_cselect_b32 s18, 0x800, s18
	s_cselect_b32 s19, 0, -1
	v_cvt_pk_bf16_f32 v38, v39, s0
	v_lshl_add_u64 v[0:1], v[0:1], 0, s[18:19]
	global_store_short v[0:1], v38, off
	v_cvt_pk_bf16_f32 v38, v40, s0
	v_lshl_add_u64 v[0:1], v[0:1], 0, s[18:19]
	global_store_short v[0:1], v38, off
	v_cvt_pk_bf16_f32 v2, v41, s0
	v_lshl_add_u64 v[0:1], v[0:1], 0, s[18:19]
	global_store_short v[0:1], v2, off
	s_branch .LBB0_778

; __device__ __forceinline__ void scan_phase(const Params& P, int l, LAS unsigned char* lds) {
;     ...
;                 if (it >= 0) {
;                     const LAS unsigned char* sl = lds + (it & 1) * SLOT;
;                     const int n0 = it * TS; const int plo = dir ? (n0 < 256 ? 256 - TS - n0 : TPB + 256 - TS - n0) : n0;
;                     u32x4 fw[4], fq[4]; u32x2 fk[8];
; #pragma unroll
;                     for (int j = 0; j < 4; ++j) { fw[j] = *(const LAS u32x4*)(sl + (j * 64 + lane) * 16); fq[j] = *(const LAS u32x4*)(sl + 4096 + (j * 64 + lane) * 16); }
; #pragma unroll
;                     for (int m = 0; m < 8; ++m) fk[m] = *(const LAS u32x2*)(sl + 8192 + (m * 64 + lane) * 8);
;                     const u32x2 fa = *(const LAS u32x2*)(sl + 12288 + lane * 8), ft = *(const LAS u32x2*)(sl + 12800 + lane * 8);
;                     const f32x4 b4 = *(const LAS f32x4*)(sl + 13312 + lane * 16), v4 = *(const LAS f32x4*)(sl + 14336 + lane * 16);
;                     const float egC = *(const LAS float*)(sl + 15360);
;                     bf16x8 sf[4];
; #pragma unroll
;                     for (int j = 0; j < 4; ++j) sf[j] = __builtin_bit_cast(bf16x8, (u32x4){pk2n(St[2 * j][0], St[2 * j][1]), pk2n(St[2 * j][2], St[2 * j][3]), pk2n(St[2 * j + 1][0], St[2 * j + 1][1]), pk2n(St[2 * j + 1][2], St[2 * j + 1][3])});
;                     const bf16x8 bv = __builtin_bit_cast(bf16x8, (u32x4){pk2n(b4[0] * v4[0], b4[1] * v4[1]), pk2n(b4[2] * v4[2], b4[3] * v4[3]), 0u, 0u});
;                     const bf16x8 FT8 = __builtin_bit_cast(bf16x8, (u32x4){ft[0], ft[1], 0u, 0u}), FA8 = __builtin_bit_cast(bf16x8, (u32x4){fa[0], fa[1], 0u, 0u});
;                     const f32x4 U = __builtin_amdgcn_mfma_f32_16x16x32_bf16(FT8, bv, zero4, 0, 0, 0);
;                     f32x4 Pw = zero4, O = zero4;
; #pragma unroll
;                     for (int j = 0; j < 4; ++j) { Pw = __builtin_amdgcn_mfma_f32_16x16x32_bf16(__builtin_bit_cast(bf16x8, fw[j]), sf[j], Pw, 0, 0, 0);
;                         O = __builtin_amdgcn_mfma_f32_16x16x32_bf16(__builtin_bit_cast(bf16x8, fq[j]), sf[j], O, 0, 0, 0); }
;                     const f32x4 Vn = U - Pw;
;                     const bf16x8 vn8 = __builtin_bit_cast(bf16x8, (u32x4){pk2n(Vn[0], Vn[1]), pk2n(Vn[2], Vn[3]), 0u, 0u});
;                     O = __builtin_amdgcn_mfma_f32_16x16x32_bf16(FA8, vn8, O, 0, 0, 0);
; #pragma unroll
.LBB0_785:
	s_cmp_lt_i32 s9, 0
	s_cbranch_scc1 .LBB0_784
	s_setprio 1
	s_bitcmp1_b32 s9, 0
	s_cselect_b32 s15, 0x6500, 0
	s_add_i32 s19, s15, 0
	v_add_u32_e32 v0, s19, v46
	ds_read_b128 v[38:41], v0
	ds_read_b128 v[60:63], v0 offset:1024
	ds_read_b128 v[64:67], v0 offset:4096
	ds_read_b128 v[68:71], v0 offset:5120
	ds_read_b128 v[72:75], v0 offset:2048
	ds_read_b128 v[76:79], v0 offset:3072
	ds_read_b128 v[80:83], v0 offset:6144
	ds_read_b128 v[84:87], v0 offset:7168
	v_cvt_pk_bf16_f32 v120, v4, v5
	v_cvt_pk_bf16_f32 v121, v6, v7
	v_cvt_pk_bf16_f32 v122, v8, v9
	v_cvt_pk_bf16_f32 v123, v10, v11
	v_add_u32_e32 v1, s19, v48
	ds_read2st64_b64 v[100:103], v1 offset0:16 offset1:17
	ds_read2st64_b64 v[104:107], v1 offset0:18 offset1:19
	ds_read2st64_b64 v[108:111], v1 offset0:20 offset1:21
	ds_read2st64_b64 v[112:115], v1 offset0:22 offset1:23
	ds_read2st64_b64 v[116:119], v1 offset0:24 offset1:25
	s_waitcnt lgkmcnt(12)
	v_mfma_f32_16x16x32_bf16 v[38:41], v[38:41], v[120:123], 0
	v_cvt_pk_bf16_f32 v132, v16, v17
	v_cvt_pk_bf16_f32 v133, v18, v19
	v_cvt_pk_bf16_f32 v134, v12, v13
	s_waitcnt lgkmcnt(10)
	v_mfma_f32_16x16x32_bf16 v[64:67], v[64:67], v[120:123], 0
	v_cvt_pk_bf16_f32 v135, v14, v15
	ds_read_b128 v[124:127], v0 offset:13312
	ds_read_b128 v[128:131], v0 offset:14336
	v_mov_b32_e32 v0, s19
	v_mfma_f32_16x16x32_bf16 v[38:41], v[60:63], v[132:135], v[38:41]
	v_cvt_pk_bf16_f32 v60, v24, v25
	v_cvt_pk_bf16_f32 v61, v26, v27
	v_cvt_pk_bf16_f32 v62, v20, v21
	s_waitcnt lgkmcnt(11)
	v_mfma_f32_16x16x32_bf16 v[64:67], v[68:71], v[132:135], v[64:67]
	v_cvt_pk_bf16_f32 v63, v22, v23
	ds_read_b32 v42, v0 offset:15360
	s_waitcnt lgkmcnt(1)
	v_pk_mul_f32 v[0:1], v[124:125], v[128:129]
	v_mfma_f32_16x16x32_bf16 v[38:41], v[72:75], v[60:63], v[38:41]
	v_mul_f32_e64 v72, v126, v130
	v_mul_f32_e64 v73, v127, v131
	v_cvt_pk_bf16_f32 v68, v32, v33
	v_cvt_pk_bf16_f32 v69, v34, v35
	v_mfma_f32_16x16x32_bf16 v[60:63], v[80:83], v[60:63], v[64:67]
	v_cvt_pk_bf16_f32 v70, v28, v29
	v_cvt_pk_bf16_f32 v71, v30, v31
	v_cvt_pk_bf16_f32 v0, v0, v1
	v_mov_b32_e32 v64, v118
	v_mov_b32_e32 v65, v119
	v_mov_b32_e32 v66, v3
	v_mov_b32_e32 v67, v3
	v_cvt_pk_bf16_f32 v1, v72, v73
	v_mov_b32_e32 v2, v3
	v_mfma_f32_16x16x32_bf16 v[38:41], v[76:79], v[68:71], v[38:41]
	s_waitcnt lgkmcnt(0)
	v_pk_mul_f32 v[6:7], v[6:7], v[42:43] op_sel_hi:[1,0]
	v_pk_mul_f32 v[4:5], v[4:5], v[42:43] op_sel_hi:[1,0]
	v_pk_mul_f32 v[10:11], v[10:11], v[42:43] op_sel_hi:[1,0]
	v_mfma_f32_16x16x32_bf16 v[64:67], v[64:67], v[0:3], 0
	v_mul_f32_e64 v8, v8, v42
	v_mul_f32_e64 v9, v9, v42
	v_pk_mul_f32 v[18:19], v[18:19], v[42:43] op_sel_hi:[1,0]
	v_pk_mul_f32 v[16:17], v[16:17], v[42:43] op_sel_hi:[1,0]
	v_pk_mul_f32 v[14:15], v[14:15], v[42:43] op_sel_hi:[1,0]
	v_pk_mul_f32 v[12:13], v[12:13], v[42:43] op_sel_hi:[1,0]
	s_nop 1
	v_sub_f32_e32 v0, v65, v39
	v_sub_f32_e32 v38, v64, v38
	v_sub_f32_e32 v1, v67, v41
	v_sub_f32_e32 v2, v66, v40
	v_cvt_pk_bf16_f32 v0, v38, v0
	v_mov_b32_e32 v38, v100
	v_mov_b32_e32 v39, v101
	v_mov_b32_e32 v40, v3
	v_mov_b32_e32 v41, v3
	v_mov_b32_e32 v64, v102
	v_mov_b32_e32 v65, v103
	v_mov_b32_e32 v66, v3
	v_mov_b32_e32 v67, v3
	v_cvt_pk_bf16_f32 v1, v2, v1
	v_mov_b32_e32 v2, v3
	s_sub_i32 s15, s8, 64
	v_pk_mul_f32 v[26:27], v[26:27], v[42:43] op_sel_hi:[1,0]
	v_mfma_f32_16x16x32_bf16 v[4:7], v[38:41], v[0:3], v[4:7]
	v_mov_b32_e32 v38, v104
	v_mov_b32_e32 v39, v105
	v_pk_mul_f32 v[24:25], v[24:25], v[42:43] op_sel_hi:[1,0]
	v_mfma_f32_16x16x32_bf16 v[8:11], v[64:67], v[0:3], v[8:11]
	v_mov_b32_e32 v64, v106
	v_mov_b32_e32 v65, v107
	v_pk_mul_f32 v[22:23], v[22:23], v[42:43] op_sel_hi:[1,0]
	v_mfma_f32_16x16x32_bf16 v[16:19], v[38:41], v[0:3], v[16:19]
	v_mov_b32_e32 v38, v108
	v_mov_b32_e32 v39, v109
	v_pk_mul_f32 v[20:21], v[20:21], v[42:43] op_sel_hi:[1,0]
	v_mfma_f32_16x16x32_bf16 v[12:15], v[64:67], v[0:3], v[12:15]
	v_mov_b32_e32 v64, v110
	v_mov_b32_e32 v65, v111
	s_cmp_lt_u32 s9, 16
	v_mfma_f32_16x16x32_bf16 v[24:27], v[38:41], v[0:3], v[24:27]
	v_mov_b32_e32 v118, v3
	v_mov_b32_e32 v38, v112
	v_mov_b32_e32 v39, v113
	v_mfma_f32_16x16x32_bf16 v[20:23], v[64:67], v[0:3], v[20:23]
	v_mov_b32_e32 v64, v114
	v_mov_b32_e32 v65, v115
	v_mov_b32_e32 v119, v3
	s_cselect_b32 s18, 0xf0, s93
	v_mfma_f32_16x16x32_bf16 v[60:63], v[84:87], v[68:71], v[60:63]
	s_add_i32 s20, s18, s14
	s_and_b64 s[18:19], vcc, exec
	v_pk_mul_f32 v[34:35], v[34:35], v[42:43] op_sel_hi:[1,0]
	v_pk_mul_f32 v[32:33], v[32:33], v[42:43] op_sel_hi:[1,0]
	v_pk_mul_f32 v[30:31], v[30:31], v[42:43] op_sel_hi:[1,0]
	v_pk_mul_f32 v[28:29], v[28:29], v[42:43] op_sel_hi:[1,0]
	s_cselect_b32 s15, s15, s20
	v_mfma_f32_16x16x32_bf16 v[32:35], v[38:41], v[0:3], v[32:35]
	s_or_b32 s15, s15, 15
	v_mfma_f32_16x16x32_bf16 v[28:31], v[64:67], v[0:3], v[28:31]
	v_mfma_f32_16x16x32_bf16 v[38:41], v[116:119], v[0:3], v[60:63]
	v_add_u32_e32 v2, s8, v45
	v_sub_u32_e32 v0, s15, v45
	v_subrev_u32_e32 v1, 64, v2
	v_cndmask_b32_e32 v0, v0, v1, vcc
	v_ashrrev_i32_e32 v1, 31, v0
	v_lshl_add_u64 v[0:1], s[16:17], 0, v[0:1]
	v_lshlrev_b64 v[0:1], 11, v[0:1]
	s_nop 0
	v_cvt_pk_bf16_f32 v38, v38, s0
	v_lshl_add_u64 v[0:1], v[36:37], 0, v[0:1]
	global_store_short v[0:1], v38, off
	s_and_b64 s[18:19], vcc, exec
	s_mov_b32 s18, 0xfffff800
	s_cselect_b32 s18, 0x800, s18
	s_cselect_b32 s19, 0, -1
	v_cvt_pk_bf16_f32 v38, v39, s0
	v_lshl_add_u64 v[0:1], v[0:1], 0, s[18:19]
	global_store_short v[0:1], v38, off
	v_cvt_pk_bf16_f32 v38, v40, s0
	v_lshl_add_u64 v[0:1], v[0:1], 0, s[18:19]
	global_store_short v[0:1], v38, off
	v_cvt_pk_bf16_f32 v2, v41, s0
	v_lshl_add_u64 v[0:1], v[0:1], 0, s[18:19]
	global_store_short v[0:1], v2, off
	s_branch .LBB0_784

; __device__ __forceinline__ unsigned xcc_id() { return (unsigned)__builtin_amdgcn_s_getreg((3 << 11) | 20) & 0xFu; }
; __device__ __forceinline__ void gbar_impl(unsigned* bar, unsigned& gen, unsigned nloc, unsigned nx) {
;     asm volatile("s_waitcnt vmcnt(0)" ::: "memory");
;     __syncthreads();
;     gen += 1u;
;     if (threadIdx.x == 0) {
;         __builtin_amdgcn_s_waitcnt(0);
;         const unsigned x = xcc_id();
;         const unsigned old = __hip_atomic_fetch_add(bar + XB_SUB(x), 1u, __ATOMIC_RELAXED, __HIP_MEMORY_SCOPE_AGENT);
.LBB0_788:
	s_setprio 0
	s_waitcnt vmcnt(0)
	s_barrier
	s_mov_b64 s[4:5], exec
	v_readlane_b32 s6, v253, 12
	v_readlane_b32 s7, v253, 13
	v_readlane_b32 s18, v251, 56
	s_and_b64 s[6:7], s[4:5], s[6:7]
	v_readlane_b32 s16, v251, 53
	v_readlane_b32 s19, v251, 57
	s_movk_i32 s37, 0x1800
	s_mov_b32 s40, 0x1400000
	s_mov_b32 s41, 0x1800000
	s_mov_b32 s93, 0x1c00000
	s_mov_b64 exec, s[6:7]
	s_cbranch_execz .LBB0_806
	s_mov_b64 s[6:7], exec
	s_waitcnt vmcnt(4)
	v_mbcnt_lo_u32_b32 v0, s6, 0
	v_mbcnt_hi_u32_b32 v0, s7, v0
	s_waitcnt vmcnt(0) expcnt(0) lgkmcnt(0)
	s_getreg_b32 s10, hwreg(HW_REG_XCC_ID, 0, 4)
	v_cmp_eq_u32_e32 vcc, 0, v0
	s_and_saveexec_b64 s[8:9], vcc
	s_cbranch_execz .LBB0_791
	s_lshl_b32 s10, s10, 8
	s_and_b32 s10, s10, 0xf00
	v_readlane_b32 s12, v252, 40
	v_readlane_b32 s13, v252, 41
	s_add_u32 s10, s12, s10
	s_addc_u32 s11, s13, 0
	s_bcnt1_i32_b64 s6, s[6:7]
	v_mov_b32_e32 v1, s6
	global_atomic_add v1, v221, v1, s[10:11] sc0
